# phase_mod silu staging: 2 pointer s_loads once and the 18 per-thread loads in flight together with counted vmcnt waits (was 18 serial s_load + load round trips per workgroup)
# speedup vs baseline: 1.0116x; 1.0103x over previous
.LBB0_1316:
	v_mov_b32_e32 v31, v163
	s_movk_i32 s0, 0x2400
	s_nop 0
	v_cmp_gt_i32_e32 vcc, s0, v31
	s_and_saveexec_b64 s[4:5], vcc
	s_cbranch_execz .LBB0_1323
	v_readlane_b32 s0, v254, 25
	v_readlane_b32 s1, v254, 26
	s_load_dwordx2 s[6:7], s[0:1], 0x48
	s_load_dwordx2 s[8:9], s[0:1], 0x50
	v_lshlrev_b32_e32 v0, 2, v31
	s_waitcnt lgkmcnt(0)
	global_load_dword v98, v0, s[8:9]
	global_load_dword v99, v0, s[8:9] offset:2048
	global_load_dword v100, v0, s[6:7]
	global_load_dword v101, v0, s[6:7] offset:2048
	s_add_u32 s6, s6, 0x1000
	s_addc_u32 s7, s7, 0
	global_load_dword v102, v0, s[6:7]
	global_load_dword v103, v0, s[6:7] offset:2048
	s_add_u32 s6, s6, 0x1000
	s_addc_u32 s7, s7, 0
	global_load_dword v104, v0, s[6:7]
	global_load_dword v105, v0, s[6:7] offset:2048
	s_add_u32 s6, s6, 0x1000
	s_addc_u32 s7, s7, 0
	global_load_dword v106, v0, s[6:7]
	global_load_dword v107, v0, s[6:7] offset:2048
	s_add_u32 s6, s6, 0x1000
	s_addc_u32 s7, s7, 0
	global_load_dword v108, v0, s[6:7]
	global_load_dword v109, v0, s[6:7] offset:2048
	s_add_u32 s6, s6, 0x1000
	s_addc_u32 s7, s7, 0
	global_load_dword v110, v0, s[6:7]
	global_load_dword v111, v0, s[6:7] offset:2048
	s_add_u32 s6, s6, 0x1000
	s_addc_u32 s7, s7, 0
	global_load_dword v112, v0, s[6:7]
	global_load_dword v113, v0, s[6:7] offset:2048
	s_add_u32 s6, s6, 0x1000
	s_addc_u32 s7, s7, 0
	global_load_dword v114, v0, s[6:7]
	global_load_dword v115, v0, s[6:7] offset:2048
	s_waitcnt vmcnt(17)
	v_mul_f32_e32 v2, 0xbfb8aa3b, v98
	v_exp_f32_e32 v2, v2
	s_nop 0
	v_add_f32_e32 v2, 1.0, v2
	v_rcp_f32_e32 v2, v2
	s_nop 0
	v_mul_f32_e32 v3, v98, v2
	ds_write_b32 v0, v3
	s_waitcnt vmcnt(16)
	v_mul_f32_e32 v2, 0xbfb8aa3b, v99
	v_exp_f32_e32 v2, v2
	s_nop 0
	v_add_f32_e32 v2, 1.0, v2
	v_rcp_f32_e32 v2, v2
	s_nop 0
	v_mul_f32_e32 v3, v99, v2
	ds_write_b32 v0, v3 offset:2048
	s_waitcnt vmcnt(15)
	v_mul_f32_e32 v2, 0xbfb8aa3b, v100
	v_exp_f32_e32 v2, v2
	s_nop 0
	v_add_f32_e32 v2, 1.0, v2
	v_rcp_f32_e32 v2, v2
	s_nop 0
	v_mul_f32_e32 v3, v100, v2
	ds_write_b32 v0, v3 offset:4096
	s_waitcnt vmcnt(14)
	v_mul_f32_e32 v2, 0xbfb8aa3b, v101
	v_exp_f32_e32 v2, v2
	s_nop 0
	v_add_f32_e32 v2, 1.0, v2
	v_rcp_f32_e32 v2, v2
	s_nop 0
	v_mul_f32_e32 v3, v101, v2
	ds_write_b32 v0, v3 offset:6144
	s_waitcnt vmcnt(13)
	v_mul_f32_e32 v2, 0xbfb8aa3b, v102
	v_exp_f32_e32 v2, v2
	s_nop 0
	v_add_f32_e32 v2, 1.0, v2
	v_rcp_f32_e32 v2, v2
	s_nop 0
	v_mul_f32_e32 v3, v102, v2
	ds_write_b32 v0, v3 offset:8192
	s_waitcnt vmcnt(12)
	v_mul_f32_e32 v2, 0xbfb8aa3b, v103
	v_exp_f32_e32 v2, v2
	s_nop 0
	v_add_f32_e32 v2, 1.0, v2
	v_rcp_f32_e32 v2, v2
	s_nop 0
	v_mul_f32_e32 v3, v103, v2
	ds_write_b32 v0, v3 offset:10240
	s_waitcnt vmcnt(11)
	v_mul_f32_e32 v2, 0xbfb8aa3b, v104
	v_exp_f32_e32 v2, v2
	s_nop 0
	v_add_f32_e32 v2, 1.0, v2
	v_rcp_f32_e32 v2, v2
	s_nop 0
	v_mul_f32_e32 v3, v104, v2
	ds_write_b32 v0, v3 offset:12288
	s_waitcnt vmcnt(10)
	v_mul_f32_e32 v2, 0xbfb8aa3b, v105
	v_exp_f32_e32 v2, v2
	s_nop 0
	v_add_f32_e32 v2, 1.0, v2
	v_rcp_f32_e32 v2, v2
	s_nop 0
	v_mul_f32_e32 v3, v105, v2
	ds_write_b32 v0, v3 offset:14336
	s_waitcnt vmcnt(9)
	v_mul_f32_e32 v2, 0xbfb8aa3b, v106
	v_exp_f32_e32 v2, v2
	s_nop 0
	v_add_f32_e32 v2, 1.0, v2
	v_rcp_f32_e32 v2, v2
	s_nop 0
	v_mul_f32_e32 v3, v106, v2
	ds_write_b32 v0, v3 offset:16384
	s_waitcnt vmcnt(8)
	v_mul_f32_e32 v2, 0xbfb8aa3b, v107
	v_exp_f32_e32 v2, v2
	s_nop 0
	v_add_f32_e32 v2, 1.0, v2
	v_rcp_f32_e32 v2, v2
	s_nop 0
	v_mul_f32_e32 v3, v107, v2
	ds_write_b32 v0, v3 offset:18432
	s_waitcnt vmcnt(7)
	v_mul_f32_e32 v2, 0xbfb8aa3b, v108
	v_exp_f32_e32 v2, v2
	s_nop 0
	v_add_f32_e32 v2, 1.0, v2
	v_rcp_f32_e32 v2, v2
	s_nop 0
	v_mul_f32_e32 v3, v108, v2
	ds_write_b32 v0, v3 offset:20480
	s_waitcnt vmcnt(6)
	v_mul_f32_e32 v2, 0xbfb8aa3b, v109
	v_exp_f32_e32 v2, v2
	s_nop 0
	v_add_f32_e32 v2, 1.0, v2
	v_rcp_f32_e32 v2, v2
	s_nop 0
	v_mul_f32_e32 v3, v109, v2
	ds_write_b32 v0, v3 offset:22528
	s_waitcnt vmcnt(5)
	v_mul_f32_e32 v2, 0xbfb8aa3b, v110
	v_exp_f32_e32 v2, v2
	s_nop 0
	v_add_f32_e32 v2, 1.0, v2
	v_rcp_f32_e32 v2, v2
	s_nop 0
	v_mul_f32_e32 v3, v110, v2
	ds_write_b32 v0, v3 offset:24576
	s_waitcnt vmcnt(4)
	v_mul_f32_e32 v2, 0xbfb8aa3b, v111
	v_exp_f32_e32 v2, v2
	s_nop 0
	v_add_f32_e32 v2, 1.0, v2
	v_rcp_f32_e32 v2, v2
	s_nop 0
	v_mul_f32_e32 v3, v111, v2
	ds_write_b32 v0, v3 offset:26624
	s_waitcnt vmcnt(3)
	v_mul_f32_e32 v2, 0xbfb8aa3b, v112
	v_exp_f32_e32 v2, v2
	s_nop 0
	v_add_f32_e32 v2, 1.0, v2
	v_rcp_f32_e32 v2, v2
	s_nop 0
	v_mul_f32_e32 v3, v112, v2
	ds_write_b32 v0, v3 offset:28672
	s_waitcnt vmcnt(2)
	v_mul_f32_e32 v2, 0xbfb8aa3b, v113
	v_exp_f32_e32 v2, v2
	s_nop 0
	v_add_f32_e32 v2, 1.0, v2
	v_rcp_f32_e32 v2, v2
	s_nop 0
	v_mul_f32_e32 v3, v113, v2
	ds_write_b32 v0, v3 offset:30720
	s_waitcnt vmcnt(1)
	v_mul_f32_e32 v2, 0xbfb8aa3b, v114
	v_exp_f32_e32 v2, v2
	s_nop 0
	v_add_f32_e32 v2, 1.0, v2
	v_rcp_f32_e32 v2, v2
	s_nop 0
	v_mul_f32_e32 v3, v114, v2
	ds_write_b32 v0, v3 offset:32768
	s_waitcnt vmcnt(0)
	v_mul_f32_e32 v2, 0xbfb8aa3b, v115
	v_exp_f32_e32 v2, v2
	s_nop 0
	v_add_f32_e32 v2, 1.0, v2
	v_rcp_f32_e32 v2, v2
	s_nop 0
	v_mul_f32_e32 v3, v115, v2
	ds_write_b32 v0, v3 offset:34816
